# strategy 8 MFMA-LDS interleave: K fragments of the first QK chain read first, counted lgkmcnt ladder lets MFMAs start on first arrival (SEL, MLA)
# baseline (speedup 1.0000x reference)
; #define MFMA32(a, b, c) __builtin_amdgcn_mfma_f32_32x32x16_bf16((a), (b), (c), 0, 0, 0)
; #define lds fresh_lds(lds0)
; template <int DQK, int MODE> ...
;     ...
;             {
;                 const unsigned kaddr = (unsigned)(unsigned long)(lds + AT_K + cur * KBUF) + (unsigned)(r32 * KP2 + hi * 16);
;                 const unsigned vaddr = (unsigned)(unsigned long)(lds + AT_V + cur * VBUF) + (unsigned)((4 * hi + ((lane & 15) >> 2)) * VP2 + 32 * ((lane >> 4) & 1) + 8 * (lane & 3));
; #pragma unroll
;                 for (int kb = 0; kb < 2; ++kb)
; #pragma unroll
;                     for (int ks = 0; ks < NKS; ++ks) asm volatile("ds_read_b128 %0, %1 offset:%2" : "=v"(ka[kb][ks]) : "v"(kaddr), "n"(kb * 32 * KP2 + ks * 32) : "memory");
; #pragma unroll
;                 for (int s2 = 0; s2 < 2; ++s2)
; #pragma unroll
;                     for (int d0 = 0; d0 < 2; ++d0) {
;                         asm volatile("ds_read_b64_tr_b16 %0, %1 offset:%2" : "=v"(vlo[0][s2][d0]) : "v"(vaddr), "n"(16 * s2 * VP2 + 64 * d0) : "memory");
;                         asm volatile("ds_read_b64_tr_b16 %0, %1 offset:%2" : "=v"(vhi[0][s2][d0]) : "v"(vaddr), "n"(16 * s2 * VP2 + 64 * d0 + 8 * VP2) : "memory");
;                     }
;                 asm volatile("s_waitcnt lgkmcnt(8)" ::: "memory");
; #pragma unroll
;                 for (int kb = 0; kb < 2; ++kb)
; #pragma unroll
;                     for (int ks = 0; ks < NKS; ++ks) asm volatile("" : "+v"(ka[kb][ks]));
;                 s[0] = (f32x16){}; s[1] = (f32x16){};
;                 __builtin_amdgcn_s_setprio(1);
; #pragma unroll
;                 for (int ks = 0; ks < NKS; ++ks) { s[0] = MFMA32(ka[0][ks], qf[ks], s[0]); s[1] = MFMA32(ka[1][ks], qf[ks], s[1]); }
.LBB0_1311:
	s_and_b32 s52, s50, 3
	s_sub_i32 s4, s51, 63
	s_cmp_gt_i32 s4, s49
	s_cbranch_scc1 .LBB0_1319
	s_mul_i32 s4, s52, 0x2400
	s_add_i32 s4, s1, s4
	v_add_u32_e32 v52, s4, v131
	s_add_i32 s4, s4, 0x9000
	v_add_u32_e32 v136, s4, v130
	ds_read_b128 v[48:51], v52 offset:0x1200
	ds_read_b128 v[68:71], v52 offset:0x1220
	ds_read_b128 v[72:75], v52 offset:0x1240
	ds_read_b128 v[76:79], v52 offset:0x1260
	ds_read_b128 v[64:67], v52 offset:0
	ds_read_b128 v[104:107], v52 offset:32
	ds_read_b128 v[108:111], v52 offset:64
	ds_read_b128 v[132:135], v52 offset:0x60
	ds_read_b64_tr_b16 v[116:117], v136 offset:0
	ds_read_b64_tr_b16 v[118:119], v136 offset:0x480
	ds_read_b64_tr_b16 v[112:113], v136 offset:64
	ds_read_b64_tr_b16 v[114:115], v136 offset:0x4c0
	ds_read_b64_tr_b16 v[100:101], v136 offset:0x900
	ds_read_b64_tr_b16 v[102:103], v136 offset:0xd80
	ds_read_b64_tr_b16 v[96:97], v136 offset:0x940
	s_waitcnt lgkmcnt(14)
	s_setprio 1
	v_mfma_f32_32x32x16_bf16 v[48:63], v[48:51], v[84:87], 0
	ds_read_b64_tr_b16 v[98:99], v136 offset:0xdc0
	s_waitcnt lgkmcnt(14)
	v_mfma_f32_32x32x16_bf16 v[48:63], v[68:71], v[80:83], v[48:63]
	s_waitcnt lgkmcnt(13)
	v_mfma_f32_32x32x16_bf16 v[48:63], v[72:75], v[10:13], v[48:63]
	s_waitcnt lgkmcnt(12)
	v_mfma_f32_32x32x16_bf16 v[48:63], v[76:79], v[6:9], v[48:63]
	s_setprio 0
	s_waitcnt lgkmcnt(8)
	v_mfma_f32_32x32x16_bf16 v[64:79], v[64:67], v[84:87], 0
	ds_read_b64_tr_b16 v[124:125], v136 offset:0x1200
	ds_read_b64_tr_b16 v[126:127], v136 offset:0x1680
	ds_read_b64_tr_b16 v[120:121], v136 offset:0x1240
	ds_read_b64_tr_b16 v[122:123], v136 offset:0x16c0
	s_cmp_le_i32 s51, s48
	v_mfma_f32_32x32x16_bf16 v[64:79], v[104:107], v[80:83], v[64:79]
	v_mfma_f32_32x32x16_bf16 v[64:79], v[108:111], v[10:13], v[64:79]
	ds_read_b64_tr_b16 v[108:109], v136 offset:0x1b00
	ds_read_b64_tr_b16 v[110:111], v136 offset:0x1f80
	ds_read_b64_tr_b16 v[104:105], v136 offset:0x1b40
	ds_read_b64_tr_b16 v[106:107], v136 offset:0x1fc0
	v_mfma_f32_32x32x16_bf16 v[64:79], v[132:135], v[6:9], v[64:79]
	s_cbranch_scc1 .LBB0_1314
	v_add_u32_e32 v132, s51, v128
	v_subrev_u32_e32 v133, 63, v132
	v_cmp_le_i32_e32 vcc, v133, v15
	s_nop 7
	v_cndmask_b32_e32 v64, v204, v64, vcc
	v_cmp_lt_i32_e32 vcc, v133, v15
	v_subrev_u32_e32 v133, 61, v132
	s_nop 0
	v_cndmask_b32_e32 v65, v204, v65, vcc
	v_cmp_le_i32_e32 vcc, v133, v15
	v_subrev_u32_e32 v133, 60, v132
	s_nop 0
	v_cndmask_b32_e32 v66, v204, v66, vcc
	v_cmp_le_i32_e32 vcc, v133, v15
	v_subrev_u32_e32 v133, 55, v132
	s_nop 0
	v_cndmask_b32_e32 v67, v204, v67, vcc
	v_cmp_le_i32_e32 vcc, v133, v15
	v_subrev_u32_e32 v133, 54, v132
	s_nop 0
	v_cndmask_b32_e32 v68, v204, v68, vcc
	v_cmp_le_i32_e32 vcc, v133, v15
	v_subrev_u32_e32 v133, 53, v132
	s_nop 0
	v_cndmask_b32_e32 v69, v204, v69, vcc
	v_cmp_le_i32_e32 vcc, v133, v15
	v_subrev_u32_e32 v133, 52, v132
	s_nop 0
	v_cndmask_b32_e32 v70, v204, v70, vcc
	v_cmp_le_i32_e32 vcc, v133, v15
	v_subrev_u32_e32 v133, 47, v132
	s_nop 0
	v_cndmask_b32_e32 v71, v204, v71, vcc
	v_cmp_le_i32_e32 vcc, v133, v15
	v_subrev_u32_e32 v133, 46, v132
	s_nop 0
	v_cndmask_b32_e32 v72, v204, v72, vcc
	v_cmp_le_i32_e32 vcc, v133, v15
	v_subrev_u32_e32 v133, 45, v132
	s_nop 0
	v_cndmask_b32_e32 v73, v204, v73, vcc
	v_cmp_le_i32_e32 vcc, v133, v15
	v_subrev_u32_e32 v133, 44, v132
	s_nop 0
	v_cndmask_b32_e32 v74, v204, v74, vcc
	v_cmp_le_i32_e32 vcc, v133, v15
	v_subrev_u32_e32 v133, 39, v132
	s_nop 0
	v_cndmask_b32_e32 v75, v204, v75, vcc
	v_cmp_le_i32_e32 vcc, v133, v15
	v_subrev_u32_e32 v133, 38, v132
	s_nop 0
	v_cndmask_b32_e32 v76, v204, v76, vcc
	v_cmp_le_i32_e32 vcc, v133, v15
	v_subrev_u32_e32 v133, 37, v132
	s_nop 0
	v_cndmask_b32_e32 v77, v204, v77, vcc
	v_cmp_le_i32_e32 vcc, v133, v15
	v_subrev_u32_e32 v133, 36, v132
	s_nop 0
	v_cndmask_b32_e32 v78, v204, v78, vcc
	v_cmp_le_i32_e32 vcc, v133, v15
	v_subrev_u32_e32 v133, 31, v132
	s_nop 0
	v_cndmask_b32_e32 v79, v204, v79, vcc
	v_cmp_le_i32_e32 vcc, v133, v15
	v_subrev_u32_e32 v133, 30, v132
	s_nop 0
	v_cndmask_b32_e32 v48, v204, v48, vcc
	v_cmp_le_i32_e32 vcc, v133, v15
	v_subrev_u32_e32 v133, 29, v132
	s_nop 0
	v_cndmask_b32_e32 v49, v204, v49, vcc
	v_cmp_le_i32_e32 vcc, v133, v15
	v_subrev_u32_e32 v133, 28, v132
	s_nop 0
	v_cndmask_b32_e32 v50, v204, v50, vcc
	v_cmp_le_i32_e32 vcc, v133, v15
	v_subrev_u32_e32 v133, 23, v132
	s_nop 0
	v_cndmask_b32_e32 v51, v204, v51, vcc
	v_cmp_le_i32_e32 vcc, v133, v15
	v_subrev_u32_e32 v133, 22, v132
	s_nop 0
	v_cndmask_b32_e32 v52, v204, v52, vcc
	v_cmp_le_i32_e32 vcc, v133, v15
	v_subrev_u32_e32 v133, 21, v132
	s_nop 0
	v_cndmask_b32_e32 v53, v204, v53, vcc
	v_cmp_le_i32_e32 vcc, v133, v15
	v_subrev_u32_e32 v133, 20, v132
	s_nop 0
	v_cndmask_b32_e32 v54, v204, v54, vcc
	v_cmp_le_i32_e32 vcc, v133, v15
	v_add_u32_e32 v133, -15, v132
	s_nop 0
	v_cndmask_b32_e32 v55, v204, v55, vcc
	v_cmp_le_i32_e32 vcc, v133, v15
	v_add_u32_e32 v133, -14, v132
	s_nop 0
	v_cndmask_b32_e32 v56, v204, v56, vcc
	v_cmp_le_i32_e32 vcc, v133, v15
	v_add_u32_e32 v133, -13, v132
	s_nop 0
	v_cndmask_b32_e32 v57, v204, v57, vcc
	v_cmp_le_i32_e32 vcc, v133, v15
	v_add_u32_e32 v133, -12, v132
	s_nop 0
	v_cndmask_b32_e32 v58, v204, v58, vcc
	v_cmp_le_i32_e32 vcc, v133, v15
	v_add_u32_e32 v133, -7, v132
	s_nop 0
	v_cndmask_b32_e32 v59, v204, v59, vcc
	v_cmp_le_i32_e32 vcc, v133, v15
	v_add_u32_e32 v133, -6, v132
	s_nop 0
	v_cndmask_b32_e32 v60, v204, v60, vcc
	v_cmp_le_i32_e32 vcc, v133, v15
	v_add_u32_e32 v133, -5, v132
	v_add_u32_e32 v132, -4, v132
	v_cndmask_b32_e32 v61, v204, v61, vcc
	v_cmp_le_i32_e32 vcc, v133, v15
	s_nop 1
	v_cndmask_b32_e32 v62, v204, v62, vcc
	v_cmp_le_i32_e32 vcc, v132, v15
	s_nop 1
	v_cndmask_b32_e32 v63, v204, v63, vcc

; #define MFMA32(a, b, c) __builtin_amdgcn_mfma_f32_32x32x16_bf16((a), (b), (c), 0, 0, 0)
; #define lds fresh_lds(lds0)
; template <int DQK, int MODE> ...
;     ...
;             {
;                 const unsigned kaddr = (unsigned)(unsigned long)(lds + AT_K + cur * KBUF) + (unsigned)(r32 * KP2 + hi * 16);
;                 const unsigned vaddr = (unsigned)(unsigned long)(lds + AT_V + cur * VBUF) + (unsigned)((4 * hi + ((lane & 15) >> 2)) * VP2 + 32 * ((lane >> 4) & 1) + 8 * (lane & 3));
; #pragma unroll
;                 for (int kb = 0; kb < 2; ++kb)
; #pragma unroll
;                     for (int ks = 0; ks < NKS; ++ks) asm volatile("ds_read_b128 %0, %1 offset:%2" : "=v"(ka[kb][ks]) : "v"(kaddr), "n"(kb * 32 * KP2 + ks * 32) : "memory");
; #pragma unroll
;                 for (int s2 = 0; s2 < 2; ++s2)
; #pragma unroll
;                     for (int d0 = 0; d0 < 2; ++d0) {
;                         asm volatile("ds_read_b64_tr_b16 %0, %1 offset:%2" : "=v"(vlo[0][s2][d0]) : "v"(vaddr), "n"(16 * s2 * VP2 + 64 * d0) : "memory");
;                         asm volatile("ds_read_b64_tr_b16 %0, %1 offset:%2" : "=v"(vhi[0][s2][d0]) : "v"(vaddr), "n"(16 * s2 * VP2 + 64 * d0 + 8 * VP2) : "memory");
;                     }
;                 asm volatile("s_waitcnt lgkmcnt(8)" ::: "memory");
; #pragma unroll
;                 for (int kb = 0; kb < 2; ++kb)
; #pragma unroll
;                     for (int ks = 0; ks < NKS; ++ks) asm volatile("" : "+v"(ka[kb][ks]));
;                 s[0] = (f32x16){}; s[1] = (f32x16){};
;                 __builtin_amdgcn_s_setprio(1);
; #pragma unroll
;                 for (int ks = 0; ks < NKS; ++ks) { s[0] = MFMA32(ka[0][ks], qf[ks], s[0]); s[1] = MFMA32(ka[1][ks], qf[ks], s[1]); }
.LBB0_1360:
	s_and_b32 s0, s36, 3
	s_sub_i32 s1, s37, 63
	s_cmp_gt_i32 s1, s30
	s_cbranch_scc1 .LBB0_1366
	s_mul_i32 s45, s0, 0x3400
	s_add_i32 s45, s28, s45
	v_add_u32_e32 v38, s45, v146
	s_mul_i32 s1, s0, 0x2400
	s_add_i32 s1, s28, s1
	s_add_i32 s1, s1, 0xd000
	v_add_u32_e32 v135, s1, v145
	ds_read_b128 v[34:37], v38 offset:0x1a00
	ds_read_b128 v[54:57], v38 offset:0x1a20
	ds_read_b128 v[58:61], v38 offset:0x1a40
	ds_read_b128 v[62:65], v38 offset:0x1a60
	ds_read_b128 v[130:133], v38 offset:0x1a80
	ds_read_b128 v[158:161], v38 offset:0x1aa0
	ds_read_b128 v[50:53], v38 offset:0
	ds_read_b128 v[118:121], v38 offset:32
	ds_read_b128 v[122:125], v38 offset:64
	ds_read_b128 v[126:129], v38 offset:0x60
	ds_read_b128 v[148:151], v38 offset:0x80
	ds_read_b128 v[152:155], v38 offset:0xa0
	ds_read_b64_tr_b16 v[114:115], v135 offset:0
	ds_read_b64_tr_b16 v[116:117], v135 offset:0x480
	ds_read_b64_tr_b16 v[110:111], v135 offset:64
	s_waitcnt lgkmcnt(14)
	s_setprio 1
	v_mfma_f32_32x32x16_bf16 v[34:49], v[34:37], v[86:89], 0
	ds_read_b64_tr_b16 v[112:113], v135 offset:0x4c0
	s_waitcnt lgkmcnt(14)
	v_mfma_f32_32x32x16_bf16 v[34:49], v[54:57], v[82:85], v[34:49]
	ds_read_b64_tr_b16 v[106:107], v135 offset:0x900
	s_waitcnt lgkmcnt(14)
	v_mfma_f32_32x32x16_bf16 v[34:49], v[58:61], v[78:81], v[34:49]
	ds_read_b64_tr_b16 v[108:109], v135 offset:0xd80
	s_waitcnt lgkmcnt(14)
	v_mfma_f32_32x32x16_bf16 v[34:49], v[62:65], v[74:77], v[34:49]
	ds_read_b64_tr_b16 v[102:103], v135 offset:0x940
	s_waitcnt lgkmcnt(14)
	v_mfma_f32_32x32x16_bf16 v[34:49], v[130:133], v[66:69], v[34:49]
	ds_read_b64_tr_b16 v[104:105], v135 offset:0xdc0
	s_waitcnt lgkmcnt(14)
	v_mfma_f32_32x32x16_bf16 v[34:49], v[158:161], v[70:73], v[34:49]
	s_setprio 0
	s_waitcnt lgkmcnt(8)
	v_mfma_f32_32x32x16_bf16 v[50:65], v[50:53], v[86:89], 0
	ds_read_b64_tr_b16 v[130:131], v135 offset:0x1200
	ds_read_b64_tr_b16 v[132:133], v135 offset:0x1680
	s_cmp_le_i32 s37, s29
	v_mfma_f32_32x32x16_bf16 v[50:65], v[118:121], v[82:85], v[50:65]
	v_mfma_f32_32x32x16_bf16 v[50:65], v[122:125], v[78:81], v[50:65]
	v_mfma_f32_32x32x16_bf16 v[50:65], v[126:129], v[74:77], v[50:65]
	ds_read_b64_tr_b16 v[126:127], v135 offset:0x1240
	ds_read_b64_tr_b16 v[128:129], v135 offset:0x16c0
	ds_read_b64_tr_b16 v[122:123], v135 offset:0x1b00
	ds_read_b64_tr_b16 v[124:125], v135 offset:0x1f80
	ds_read_b64_tr_b16 v[118:119], v135 offset:0x1b40
	ds_read_b64_tr_b16 v[120:121], v135 offset:0x1fc0
	v_mfma_f32_32x32x16_bf16 v[50:65], v[148:151], v[66:69], v[50:65]
	v_mfma_f32_32x32x16_bf16 v[50:65], v[152:155], v[70:73], v[50:65]
	s_cbranch_scc1 .LBB0_1363
	v_add_u32_e32 v135, s37, v139
	v_subrev_u32_e32 v147, 63, v135
	v_cmp_le_i32_e32 vcc, v147, v136
	s_nop 7
	v_cndmask_b32_e32 v50, v204, v50, vcc
	v_cmp_lt_i32_e32 vcc, v147, v136
	v_subrev_u32_e32 v147, 61, v135
	s_nop 0
	v_cndmask_b32_e32 v51, v204, v51, vcc
	v_cmp_le_i32_e32 vcc, v147, v136
	v_subrev_u32_e32 v147, 60, v135
	s_nop 0
	v_cndmask_b32_e32 v52, v204, v52, vcc
	v_cmp_le_i32_e32 vcc, v147, v136
	v_subrev_u32_e32 v147, 55, v135
	s_nop 0
	v_cndmask_b32_e32 v53, v204, v53, vcc
	v_cmp_le_i32_e32 vcc, v147, v136
	v_subrev_u32_e32 v147, 54, v135
	s_nop 0
	v_cndmask_b32_e32 v54, v204, v54, vcc
	v_cmp_le_i32_e32 vcc, v147, v136
	v_subrev_u32_e32 v147, 53, v135
	s_nop 0
	v_cndmask_b32_e32 v55, v204, v55, vcc
	v_cmp_le_i32_e32 vcc, v147, v136
	v_subrev_u32_e32 v147, 52, v135
	s_nop 0
	v_cndmask_b32_e32 v56, v204, v56, vcc
	v_cmp_le_i32_e32 vcc, v147, v136
	v_subrev_u32_e32 v147, 47, v135
	s_nop 0
	v_cndmask_b32_e32 v57, v204, v57, vcc
	v_cmp_le_i32_e32 vcc, v147, v136
	v_subrev_u32_e32 v147, 46, v135
	s_nop 0
	v_cndmask_b32_e32 v58, v204, v58, vcc
	v_cmp_le_i32_e32 vcc, v147, v136
	v_subrev_u32_e32 v147, 45, v135
	s_nop 0
	v_cndmask_b32_e32 v59, v204, v59, vcc
	v_cmp_le_i32_e32 vcc, v147, v136
	v_subrev_u32_e32 v147, 44, v135
	s_nop 0
	v_cndmask_b32_e32 v60, v204, v60, vcc
	v_cmp_le_i32_e32 vcc, v147, v136
	v_subrev_u32_e32 v147, 39, v135
	s_nop 0
	v_cndmask_b32_e32 v61, v204, v61, vcc
	v_cmp_le_i32_e32 vcc, v147, v136
	v_subrev_u32_e32 v147, 38, v135
	s_nop 0
	v_cndmask_b32_e32 v62, v204, v62, vcc
	v_cmp_le_i32_e32 vcc, v147, v136
	v_subrev_u32_e32 v147, 37, v135
	s_nop 0
	v_cndmask_b32_e32 v63, v204, v63, vcc
	v_cmp_le_i32_e32 vcc, v147, v136
	v_subrev_u32_e32 v147, 36, v135
	s_nop 0
	v_cndmask_b32_e32 v64, v204, v64, vcc
	v_cmp_le_i32_e32 vcc, v147, v136
	v_subrev_u32_e32 v147, 31, v135
	s_nop 0
	v_cndmask_b32_e32 v65, v204, v65, vcc
	v_cmp_le_i32_e32 vcc, v147, v136
	v_subrev_u32_e32 v147, 30, v135
	s_nop 0
	v_cndmask_b32_e32 v34, v204, v34, vcc
	v_cmp_le_i32_e32 vcc, v147, v136
	v_subrev_u32_e32 v147, 29, v135
	s_nop 0
	v_cndmask_b32_e32 v35, v204, v35, vcc
	v_cmp_le_i32_e32 vcc, v147, v136
	v_subrev_u32_e32 v147, 28, v135
	s_nop 0
	v_cndmask_b32_e32 v36, v204, v36, vcc
	v_cmp_le_i32_e32 vcc, v147, v136
	v_subrev_u32_e32 v147, 23, v135
	s_nop 0
	v_cndmask_b32_e32 v37, v204, v37, vcc
	v_cmp_le_i32_e32 vcc, v147, v136
	v_subrev_u32_e32 v147, 22, v135
	s_nop 0
	v_cndmask_b32_e32 v38, v204, v38, vcc
	v_cmp_le_i32_e32 vcc, v147, v136
	v_subrev_u32_e32 v147, 21, v135
	s_nop 0
	v_cndmask_b32_e32 v39, v204, v39, vcc
	v_cmp_le_i32_e32 vcc, v147, v136
	v_subrev_u32_e32 v147, 20, v135
	s_nop 0
	v_cndmask_b32_e32 v40, v204, v40, vcc
	v_cmp_le_i32_e32 vcc, v147, v136
	v_add_u32_e32 v147, -15, v135
	s_nop 0
	v_cndmask_b32_e32 v41, v204, v41, vcc
	v_cmp_le_i32_e32 vcc, v147, v136
	v_add_u32_e32 v147, -14, v135
	s_nop 0
	v_cndmask_b32_e32 v42, v204, v42, vcc
	v_cmp_le_i32_e32 vcc, v147, v136
	v_add_u32_e32 v147, -13, v135
	s_nop 0
	v_cndmask_b32_e32 v43, v204, v43, vcc
	v_cmp_le_i32_e32 vcc, v147, v136
	v_add_u32_e32 v147, -12, v135
	s_nop 0
	v_cndmask_b32_e32 v44, v204, v44, vcc
	v_cmp_le_i32_e32 vcc, v147, v136
	v_add_u32_e32 v147, -7, v135
	s_nop 0
	v_cndmask_b32_e32 v45, v204, v45, vcc
	v_cmp_le_i32_e32 vcc, v147, v136
	v_add_u32_e32 v147, -6, v135
	s_nop 0
	v_cndmask_b32_e32 v46, v204, v46, vcc
	v_cmp_le_i32_e32 vcc, v147, v136
	v_add_u32_e32 v147, -5, v135
	v_add_u32_e32 v135, -4, v135
	v_cndmask_b32_e32 v47, v204, v47, vcc
	v_cmp_le_i32_e32 vcc, v147, v136
	s_nop 1
	v_cndmask_b32_e32 v48, v204, v48, vcc
	v_cmp_le_i32_e32 vcc, v135, v136
	s_nop 1
	v_cndmask_b32_e32 v49, v204, v49, vcc
